# barrier poll loops (3 team barriers + 2 flat-barrier release polls): one extra poll kept in flight half a round trip out of phase (vmcnt(1) check)
# speedup vs baseline: 1.0133x; 1.0014x over previous
.LBB0_140:
	v_mov_b32_e32 v2, 0
	global_load_dword v3, v2, s[6:7] sc1
	s_waitcnt vmcnt(0)
	v_cmp_ne_u32_e32 vcc, 0, v3
	s_cbranch_vccnz .LBB0_151
	s_mov_b32 s0, 1
	global_load_dword v3, v2, s[6:7] sc1
	s_sleep 15
	s_branch .LBB0_143

.LBB0_145:
	global_load_dword v3, v2, s[6:7] sc1
	s_add_i32 s0, s0, 1
	s_mov_b64 s[22:23], -1
	s_waitcnt vmcnt(1)
	v_cmp_ne_u32_e64 s[4:5], 0, v3
	s_branch .LBB0_142

.LBB0_219:
	s_or_b64 exec, exec, s[36:37]
	v_mov_b32_e32 v2, 0
	global_load_dword v3, v2, s[6:7] sc1
	s_waitcnt vmcnt(0)
	v_cmp_lt_u32_e32 vcc, 3, v3
	s_cbranch_vccnz .LBB0_230
	s_mov_b32 s0, 1
	global_load_dword v3, v2, s[6:7] sc1
	s_sleep 15
	s_branch .LBB0_222

.LBB0_224:
	global_load_dword v3, v2, s[6:7] sc1
	s_add_i32 s0, s0, 1
	s_mov_b64 s[36:37], -1
	s_waitcnt vmcnt(1)
	v_cmp_lt_u32_e64 s[22:23], 3, v3
	s_branch .LBB0_221

.Lpp_534:
	global_load_dword v3, v2, s[6:7] sc1
	s_sleep 15
	s_branch .LBB0_534

.LBB0_536:
	global_load_dword v3, v2, s[6:7] sc1
	s_add_i32 s0, s0, 1
	s_mov_b64 s[8:9], -1
	s_waitcnt vmcnt(1)
	v_cmp_lt_u32_e64 s[4:5], 1, v3
	s_branch .LBB0_533

.LBB0_744:
	s_or_b64 exec, exec, s[12:13]
	v_mov_b32_e32 v2, 0
	global_load_dword v3, v2, s[8:9] sc1
	s_waitcnt vmcnt(0)
	v_cmp_lt_u32_e32 vcc, 11, v3
	s_cbranch_vccnz .LBB0_755
	s_mov_b32 s0, 1
	global_load_dword v3, v2, s[8:9] sc1
	s_sleep 15
	s_branch .LBB0_747

.LBB0_749:
	global_load_dword v3, v2, s[8:9] sc1
	s_add_i32 s0, s0, 1
	s_mov_b64 s[12:13], -1
	s_waitcnt vmcnt(1)
	v_cmp_lt_u32_e64 s[10:11], 11, v3
	s_branch .LBB0_746

.LBB0_834:
	s_or_b64 exec, exec, s[12:13]
	v_mov_b32_e32 v2, 0
	global_load_dword v3, v2, s[0:1] sc1
	s_waitcnt vmcnt(0)
	v_cmp_lt_u32_e32 vcc, 15, v3
	s_cbranch_vccnz .LBB0_845
	s_mov_b32 s16, 1
	global_load_dword v3, v2, s[0:1] sc1
	s_sleep 15
	s_branch .LBB0_837

.LBB0_839:
	global_load_dword v3, v2, s[0:1] sc1
	s_add_i32 s16, s16, 1
	s_mov_b64 s[12:13], -1
	s_waitcnt vmcnt(1)
	v_cmp_lt_u32_e64 s[10:11], 15, v3
	s_branch .LBB0_836
